# kernel start: silu(c) staging loop (12 dependent load-wait iterations with kernarg reloads) replaced by 12 loads issued up front
# baseline (speedup 1.0000x reference)
.LBB0_13:
	s_and_b32 s3, s8, 0xffffffc0
	s_mov_b32 s2, -1
	v_writelane_b32 v254, s3, 5
	v_mbcnt_lo_u32_b32 v0, s2, 0
	v_mbcnt_hi_u32_b32 v0, s2, v0
	v_readlane_b32 s2, v254, 0
	v_add_u32_e32 v4, s3, v0
	s_mov_b32 s6, s2
	s_mov_b64 s[2:3], s[66:67]
	s_mov_b64 s[8:9], s[60:61]
	s_mov_b64 s[4:5], s[64:65]
	s_movk_i32 s4, 0x1800
	v_ashrrev_i32_e32 v0, 6, v4
	v_cmp_gt_i32_e32 vcc, s4, v4
	v_readfirstlane_b32 s20, v0
	s_and_saveexec_b64 s[4:5], vcc
	s_cbranch_execz .LBB0_20
	s_load_dwordx2 s[16:17], s[8:9], 0x60
	s_load_dwordx2 s[14:15], s[8:9], 0x58
	v_lshlrev_b32_e32 v2, 2, v4
	v_lshl_add_u32 v1, v4, 2, 0
	v_add_u32_e32 v3, 0x1000, v2
	v_add_u32_e32 v5, 0x2000, v2
	v_add_u32_e32 v7, 0x3000, v2
	s_waitcnt lgkmcnt(0)
	global_load_dword v34, v2, s[16:17]
	global_load_dword v35, v2, s[16:17] offset:2048
	global_load_dword v36, v3, s[16:17]
	global_load_dword v37, v3, s[16:17] offset:2048
	global_load_dword v38, v2, s[14:15]
	global_load_dword v39, v2, s[14:15] offset:2048
	global_load_dword v40, v3, s[14:15]
	global_load_dword v41, v3, s[14:15] offset:2048
	global_load_dword v42, v5, s[14:15]
	global_load_dword v43, v5, s[14:15] offset:2048
	global_load_dword v44, v7, s[14:15]
	global_load_dword v45, v7, s[14:15] offset:2048
	s_waitcnt vmcnt(11)
	v_mul_f32_e32 v46, 0xbfb8aa3b, v34
	s_waitcnt vmcnt(10)
	v_mul_f32_e32 v47, 0xbfb8aa3b, v35
	s_waitcnt vmcnt(9)
	v_mul_f32_e32 v48, 0xbfb8aa3b, v36
	s_waitcnt vmcnt(8)
	v_mul_f32_e32 v49, 0xbfb8aa3b, v37
	s_waitcnt vmcnt(7)
	v_mul_f32_e32 v50, 0xbfb8aa3b, v38
	s_waitcnt vmcnt(6)
	v_mul_f32_e32 v51, 0xbfb8aa3b, v39
	s_waitcnt vmcnt(5)
	v_mul_f32_e32 v52, 0xbfb8aa3b, v40
	s_waitcnt vmcnt(4)
	v_mul_f32_e32 v53, 0xbfb8aa3b, v41
	s_waitcnt vmcnt(3)
	v_mul_f32_e32 v54, 0xbfb8aa3b, v42
	s_waitcnt vmcnt(2)
	v_mul_f32_e32 v55, 0xbfb8aa3b, v43
	s_waitcnt vmcnt(1)
	v_mul_f32_e32 v56, 0xbfb8aa3b, v44
	s_waitcnt vmcnt(0)
	v_mul_f32_e32 v57, 0xbfb8aa3b, v45
	v_exp_f32_e32 v46, v46
	v_exp_f32_e32 v47, v47
	v_exp_f32_e32 v48, v48
	v_exp_f32_e32 v49, v49
	v_exp_f32_e32 v50, v50
	v_exp_f32_e32 v51, v51
	v_exp_f32_e32 v52, v52
	v_exp_f32_e32 v53, v53
	v_exp_f32_e32 v54, v54
	v_exp_f32_e32 v55, v55
	v_exp_f32_e32 v56, v56
	v_exp_f32_e32 v57, v57
	v_add_f32_e32 v46, 1.0, v46
	v_add_f32_e32 v47, 1.0, v47
	v_add_f32_e32 v48, 1.0, v48
	v_add_f32_e32 v49, 1.0, v49
	v_add_f32_e32 v50, 1.0, v50
	v_add_f32_e32 v51, 1.0, v51
	v_add_f32_e32 v52, 1.0, v52
	v_add_f32_e32 v53, 1.0, v53
	v_add_f32_e32 v54, 1.0, v54
	v_add_f32_e32 v55, 1.0, v55
	v_add_f32_e32 v56, 1.0, v56
	v_add_f32_e32 v57, 1.0, v57
	v_rcp_f32_e32 v46, v46
	v_rcp_f32_e32 v47, v47
	v_rcp_f32_e32 v48, v48
	v_rcp_f32_e32 v49, v49
	v_rcp_f32_e32 v50, v50
	v_rcp_f32_e32 v51, v51
	v_rcp_f32_e32 v52, v52
	v_rcp_f32_e32 v53, v53
	v_rcp_f32_e32 v54, v54
	v_rcp_f32_e32 v55, v55
	v_rcp_f32_e32 v56, v56
	v_rcp_f32_e32 v57, v57
	v_mul_f32_e32 v34, v34, v46
	v_mul_f32_e32 v35, v35, v47
	v_mul_f32_e32 v36, v36, v48
	v_mul_f32_e32 v37, v37, v49
	v_mul_f32_e32 v38, v38, v50
	v_mul_f32_e32 v39, v39, v51
	v_mul_f32_e32 v40, v40, v52
	v_mul_f32_e32 v41, v41, v53
	v_mul_f32_e32 v42, v42, v54
	v_mul_f32_e32 v43, v43, v55
	v_mul_f32_e32 v44, v44, v56
	v_mul_f32_e32 v45, v45, v57
	ds_write_b32 v1, v34
	ds_write_b32 v1, v35 offset:2048
	ds_write_b32 v1, v36 offset:4096
	ds_write_b32 v1, v37 offset:6144
	ds_write_b32 v1, v38 offset:8192
	ds_write_b32 v1, v39 offset:10240
	ds_write_b32 v1, v40 offset:12288
	ds_write_b32 v1, v41 offset:14336
	ds_write_b32 v1, v42 offset:16384
	ds_write_b32 v1, v43 offset:18432
	ds_write_b32 v1, v44 offset:20480
	ds_write_b32 v1, v45 offset:22528
